# stack9: B and H GEMM: next tile's phase-1 DMA pair issued at epilogue start; iteration 0 after an epilogue skips that pair and the phase-4 vmcnt(6) so epilogue stores drain under the K-loop
# baseline (speedup 1.0000x reference)
.LBB0_284:
	v_readlane_b32 s10, v250, 58
	v_readlane_b32 s11, v250, 59
	s_mul_i32 s86, s10, 0x10400
	s_lshl_b64 s[10:11], s[86:87], 2
	s_add_u32 s3, s96, s10
	s_addc_u32 s10, s97, s11
	s_add_u32 s12, s3, 0x1f2cd800
	s_addc_u32 s13, s10, 0
	v_writelane_b32 v249, s12, 12
	s_andn2_b64 vcc, exec, s[8:9]
	s_nop 0
	v_writelane_b32 v249, s13, 13
	v_writelane_b32 v249, s28, 14
	s_nop 1
	v_writelane_b32 v249, s29, 15
	s_cbranch_vccnz .LBB0_592
	v_ashrrev_i32_e32 v1, 31, v8
	v_lshrrev_b32_e32 v1, 26, v1
	v_add_u32_e32 v1, v8, v1
	v_ashrrev_i32_e32 v9, 6, v1
	v_bfe_i32 v1, v8, 27, 1
	v_lshlrev_b32_e32 v0, 4, v8
	v_lshrrev_b32_e32 v1, 22, v1
	v_add_u32_e32 v1, v0, v1
	v_and_b32_e32 v1, 0xfffffc00, v1
	v_sub_u32_e32 v1, v0, v1
	v_lshrrev_b32_e32 v2, 4, v1
	v_bitop3_b32 v2, v2, v1, 32 bitop3:0x6c
	v_ashrrev_i32_e32 v1, 31, v1
	v_lshrrev_b32_e32 v1, 26, v1
	v_add_u32_e32 v1, v2, v1
	v_ashrrev_i32_e32 v10, 6, v1
	v_mul_i32_i24_e32 v4, 64, v10
	v_sub_u32_e32 v2, v2, v4
	v_lshlrev_b32_e32 v3, 3, v9
	v_lshlrev_b32_e32 v1, 5, v9
	v_ashrrev_i16_sdwa v2, v227, sext(v2) dst_sel:DWORD dst_unused:UNUSED_PAD src0_sel:DWORD src1_sel:BYTE_0
	v_and_b32_e32 v3, 0x1ffff0, v3
	v_and_b32_e32 v1, 32, v1
	v_bfe_i32 v11, v2, 0, 16
	v_add_u32_e32 v1, v1, v11
	v_add_lshl_u32 v2, v10, v3, 11
	v_add_u32_e32 v0, 0x2000, v0
	v_lshl_add_u32 v144, v1, 1, v2
	v_ashrrev_i32_e32 v1, 31, v0
	v_lshrrev_b32_e32 v1, 22, v1
	v_add_u32_e32 v1, v0, v1
	v_ashrrev_i32_e32 v12, 10, v1
	v_mul_i32_i24_e32 v1, 0x400, v12
	v_sub_u32_e32 v0, v0, v1
	v_lshrrev_b32_e32 v1, 4, v0
	v_bitop3_b32 v0, v1, v0, 32 bitop3:0x6c
	v_ashrrev_i32_e32 v2, 31, v0
	v_lshrrev_b32_e32 v2, 26, v2
	v_add_u32_e32 v2, v0, v2
	v_ashrrev_i32_e32 v13, 6, v2
	v_and_b32_e32 v2, 0xc0, v2
	s_ashr_i32 s3, s56, 6
	v_sub_u32_e32 v0, v0, v2
	v_lshlrev_b32_e32 v1, 3, v12
	v_lshlrev_b32_e32 v3, 5, v12
	v_ashrrev_i16_sdwa v0, v227, sext(v0) dst_sel:DWORD dst_unused:UNUSED_PAD src0_sel:DWORD src1_sel:BYTE_0
	s_lshl_b32 s58, s3, 10
	v_and_b32_e32 v1, 0x1ffff0, v1
	v_and_b32_e32 v3, 32, v3
	v_bfe_i32 v14, v0, 0, 16
	s_add_i32 s59, s58, 0
	v_add_u32_e32 v0, v3, v14
	v_add_lshl_u32 v1, v13, v1, 11
	s_add_i32 m0, s59, 0x10000
	v_lshl_add_u32 v146, v0, 1, v1
	s_mov_b32 s101, 1
	global_load_lds_dwordx4 v144, s[38:39]
	s_add_i32 m0, s59, 0x12000
	s_ashr_i32 s57, s56, 8
	global_load_lds_dwordx4 v146, s[38:39]
	s_mov_b32 m0, s59
	s_add_i32 s60, s59, 0x2000
	global_load_lds_dwordx4 v144, s[22:23]
	s_mov_b32 m0, s60
	s_add_u32 s8, s38, 0x40000
	global_load_lds_dwordx4 v146, s[22:23]
	s_addc_u32 s9, s39, 0
	s_add_i32 m0, s59, 0x14000
	v_mov_b32_e32 v145, v177
	global_load_lds_dwordx4 v144, s[8:9]
	s_add_i32 m0, s59, 0x16000
	v_mov_b32_e32 v147, v177
	global_load_lds_dwordx4 v146, s[8:9]
	s_add_u32 s8, s22, 0x40000
	s_addc_u32 s9, s23, 0
	s_add_i32 s61, s59, 0x4000
	s_mov_b32 m0, s61
	s_add_i32 s62, s59, 0x6000
	global_load_lds_dwordx4 v144, s[8:9]
	s_mov_b32 m0, s62
	v_lshl_add_u64 v[6:7], s[38:39], 0, v[144:145]
	global_load_lds_dwordx4 v146, s[8:9]
	v_lshl_add_u64 v[4:5], s[38:39], 0, v[146:147]
	v_lshl_add_u64 v[2:3], s[22:23], 0, v[144:145]
	s_cmp_lg_u32 s57, 1
	v_lshl_add_u64 v[0:1], s[22:23], 0, v[146:147]
	s_cbranch_scc1 .LBB0_287
	s_barrier

.LBB0_288:
	s_mov_b32 s101, -2
	s_and_b64 vcc, exec, s[40:41]
	s_mov_b32 s74, s30
	s_mov_b32 s2, s34
	s_mov_b64 s[38:39], s[52:53]
	s_mov_b64 s[22:23], s[36:37]
	s_cbranch_vccnz .LBB0_589

.LBB0_296:
	s_add_u32 s38, s22, 0xfffc0080
	s_addc_u32 s39, s23, -1
	s_add_i32 s44, 0, 0x10000
	v_add_u32_e32 v140, s44, v240
	s_waitcnt lgkmcnt(0)
	ds_read_b128 v[128:131], v140
	ds_read_b128 v[132:135], v140 offset:1024
	ds_read_b128 v[136:139], v140 offset:2048
	ds_read_b128 v[140:143], v140 offset:3072
	s_cmp_eq_u32 s35, 12
	s_cselect_b32 s43, s37, s39
	s_cselect_b32 s42, s36, s38
	s_cselect_b32 s39, s53, s31
	s_cselect_b32 s38, s52, s3
	v_lshl_add_u64 v[198:199], s[22:23], 0, v[148:149]
	s_add_i32 m0, s59, 0xc000
	ds_read_b128 v[152:155], v241
	ds_read_b128 v[156:159], v241 offset:1024
	ds_read_b128 v[160:163], v241 offset:2048
	ds_read_b128 v[164:167], v241 offset:3072
	ds_read_b128 v[168:171], v241 offset:4096
	ds_read_b128 v[172:175], v241 offset:5120
	ds_read_b128 v[190:193], v241 offset:6144
	ds_read_b128 v[194:197], v241 offset:7168
	s_cmp_eq_u32 s35, s101
	s_cbranch_scc1 .Lhoist_p1_B
	global_load_lds_dwordx4 v[198:199], off
	v_lshl_add_u64 v[198:199], s[22:23], 0, v[150:151]
	s_add_i32 m0, s59, 0xe000
	s_nop 0
	global_load_lds_dwordx4 v[198:199], off
.Lhoist_p1_B:
	s_waitcnt lgkmcnt(8)
	s_barrier
	s_waitcnt lgkmcnt(0)
	s_setprio 1
	s_waitcnt lgkmcnt(0)
	v_mfma_f32_16x16x32_bf16 v[124:127], v[128:131], v[152:155], v[124:127]
	v_mfma_f32_16x16x32_bf16 v[120:123], v[136:139], v[152:155], v[120:123]
	v_mfma_f32_16x16x32_bf16 v[108:111], v[128:131], v[160:163], v[108:111]
	v_mfma_f32_16x16x32_bf16 v[104:107], v[136:139], v[160:163], v[104:107]
	v_mfma_f32_16x16x32_bf16 v[92:95], v[128:131], v[168:171], v[92:95]
	v_mfma_f32_16x16x32_bf16 v[88:91], v[136:139], v[168:171], v[88:91]
	v_mfma_f32_16x16x32_bf16 v[76:79], v[128:131], v[190:193], v[76:79]
	v_mfma_f32_16x16x32_bf16 v[72:75], v[136:139], v[190:193], v[72:75]
	v_mfma_f32_16x16x32_bf16 v[124:127], v[132:135], v[156:159], v[124:127]
	v_mfma_f32_16x16x32_bf16 v[120:123], v[140:143], v[156:159], v[120:123]
	v_mfma_f32_16x16x32_bf16 v[108:111], v[132:135], v[164:167], v[108:111]
	v_mfma_f32_16x16x32_bf16 v[104:107], v[140:143], v[164:167], v[104:107]
	v_mfma_f32_16x16x32_bf16 v[92:95], v[132:135], v[172:175], v[92:95]
	v_mfma_f32_16x16x32_bf16 v[88:91], v[140:143], v[172:175], v[88:91]
	v_mfma_f32_16x16x32_bf16 v[76:79], v[132:135], v[194:197], v[76:79]
	v_mfma_f32_16x16x32_bf16 v[72:75], v[140:143], v[194:197], v[72:75]
	s_setprio 0
	s_barrier
	s_add_i32 s46, 0, 0x14000
	s_add_i32 s44, s44, s58
	v_add_u32_e32 v176, s46, v240
	v_lshl_add_u64 v[214:215], s[38:39], 0, v[144:145]
	s_mov_b32 m0, s44
	ds_read_b128 v[198:201], v176
	ds_read_b128 v[202:205], v176 offset:1024
	ds_read_b128 v[206:209], v176 offset:2048
	ds_read_b128 v[210:213], v176 offset:3072
	global_load_lds_dwordx4 v[214:215], off
	v_lshl_add_u64 v[216:217], s[38:39], 0, v[146:147]
	s_add_i32 m0, s44, 0x2000
	s_nop 0
	global_load_lds_dwordx4 v[216:217], off
	s_barrier
	s_waitcnt lgkmcnt(0)
	s_setprio 1
	s_waitcnt lgkmcnt(0)
	v_mfma_f32_16x16x32_bf16 v[116:119], v[198:201], v[152:155], v[116:119]
	v_mfma_f32_16x16x32_bf16 v[112:115], v[206:209], v[152:155], v[112:115]
	v_mfma_f32_16x16x32_bf16 v[100:103], v[198:201], v[160:163], v[100:103]
	v_mfma_f32_16x16x32_bf16 v[96:99], v[206:209], v[160:163], v[96:99]
	v_mfma_f32_16x16x32_bf16 v[84:87], v[198:201], v[168:171], v[84:87]
	v_mfma_f32_16x16x32_bf16 v[80:83], v[206:209], v[168:171], v[80:83]
	v_mfma_f32_16x16x32_bf16 v[68:71], v[198:201], v[190:193], v[68:71]
	v_mfma_f32_16x16x32_bf16 v[64:67], v[206:209], v[190:193], v[64:67]
	v_mfma_f32_16x16x32_bf16 v[116:119], v[202:205], v[156:159], v[116:119]
	v_mfma_f32_16x16x32_bf16 v[112:115], v[210:213], v[156:159], v[112:115]
	v_mfma_f32_16x16x32_bf16 v[100:103], v[202:205], v[164:167], v[100:103]
	v_mfma_f32_16x16x32_bf16 v[96:99], v[210:213], v[164:167], v[96:99]
	v_mfma_f32_16x16x32_bf16 v[84:87], v[202:205], v[172:175], v[84:87]
	v_mfma_f32_16x16x32_bf16 v[80:83], v[210:213], v[172:175], v[80:83]
	v_mfma_f32_16x16x32_bf16 v[68:71], v[202:205], v[194:197], v[68:71]
	v_mfma_f32_16x16x32_bf16 v[64:67], v[210:213], v[194:197], v[64:67]
	s_setprio 0
	s_mov_b32 m0, s59
	v_lshl_add_u64 v[218:219], s[42:43], 0, v[144:145]
	s_barrier
	ds_read_b128 v[152:155], v241 offset:16384
	ds_read_b128 v[156:159], v241 offset:17408
	ds_read_b128 v[160:163], v241 offset:18432
	ds_read_b128 v[164:167], v241 offset:19456
	ds_read_b128 v[168:171], v241 offset:20480
	ds_read_b128 v[172:175], v241 offset:21504
	ds_read_b128 v[190:193], v241 offset:22528
	ds_read_b128 v[194:197], v241 offset:23552
	global_load_lds_dwordx4 v[218:219], off
	v_lshl_add_u64 v[220:221], s[42:43], 0, v[146:147]
	s_mov_b32 m0, s60
	s_nop 0
	global_load_lds_dwordx4 v[220:221], off
	s_barrier
	s_waitcnt lgkmcnt(0)
	s_setprio 1
	s_waitcnt lgkmcnt(0)
	v_mfma_f32_16x16x32_bf16 v[60:63], v[128:131], v[152:155], v[60:63]
	v_mfma_f32_16x16x32_bf16 v[56:59], v[136:139], v[152:155], v[56:59]
	v_mfma_f32_16x16x32_bf16 v[44:47], v[128:131], v[160:163], v[44:47]
	v_mfma_f32_16x16x32_bf16 v[40:43], v[136:139], v[160:163], v[40:43]
	v_mfma_f32_16x16x32_bf16 v[28:31], v[128:131], v[168:171], v[28:31]
	v_mfma_f32_16x16x32_bf16 v[24:27], v[136:139], v[168:171], v[24:27]
	v_mfma_f32_16x16x32_bf16 v[12:15], v[128:131], v[190:193], v[12:15]
	v_mfma_f32_16x16x32_bf16 v[8:11], v[136:139], v[190:193], v[8:11]
	v_mfma_f32_16x16x32_bf16 v[60:63], v[132:135], v[156:159], v[60:63]
	v_mfma_f32_16x16x32_bf16 v[56:59], v[140:143], v[156:159], v[56:59]
	v_mfma_f32_16x16x32_bf16 v[44:47], v[132:135], v[164:167], v[44:47]
	v_mfma_f32_16x16x32_bf16 v[40:43], v[140:143], v[164:167], v[40:43]
	v_mfma_f32_16x16x32_bf16 v[28:31], v[132:135], v[172:175], v[28:31]
	v_mfma_f32_16x16x32_bf16 v[24:27], v[140:143], v[172:175], v[24:27]
	v_mfma_f32_16x16x32_bf16 v[12:15], v[132:135], v[194:197], v[12:15]
	v_mfma_f32_16x16x32_bf16 v[8:11], v[140:143], v[194:197], v[8:11]
	s_setprio 0
	s_barrier
	s_add_u32 s44, s38, 0x40000
	s_addc_u32 s45, s39, 0
	s_add_i32 s46, s46, s58
	v_lshl_add_u64 v[128:129], s[44:45], 0, v[144:145]
	s_mov_b32 m0, s46
	s_nop 0
	global_load_lds_dwordx4 v[128:129], off
	v_lshl_add_u64 v[128:129], s[44:45], 0, v[146:147]
	s_add_i32 m0, s46, 0x2000
	s_nop 0
	global_load_lds_dwordx4 v[128:129], off
	s_cmp_eq_u32 s35, s101
	s_cbranch_scc1 .Lhoist_p4_B
	s_waitcnt vmcnt(6)
.Lhoist_p4_B:
	s_barrier
	s_setprio 1
	v_mfma_f32_16x16x32_bf16 v[52:55], v[198:201], v[152:155], v[52:55]
	v_mfma_f32_16x16x32_bf16 v[48:51], v[206:209], v[152:155], v[48:51]
	v_mfma_f32_16x16x32_bf16 v[36:39], v[198:201], v[160:163], v[36:39]
	v_mfma_f32_16x16x32_bf16 v[32:35], v[206:209], v[160:163], v[32:35]
	v_mfma_f32_16x16x32_bf16 v[20:23], v[198:201], v[168:171], v[20:23]
	v_mfma_f32_16x16x32_bf16 v[16:19], v[206:209], v[168:171], v[16:19]
	v_mfma_f32_16x16x32_bf16 v[4:7], v[198:201], v[190:193], v[4:7]
	v_mfma_f32_16x16x32_bf16 v[0:3], v[206:209], v[190:193], v[0:3]
	v_mfma_f32_16x16x32_bf16 v[52:55], v[202:205], v[156:159], v[52:55]
	v_mfma_f32_16x16x32_bf16 v[48:51], v[210:213], v[156:159], v[48:51]
	v_mfma_f32_16x16x32_bf16 v[36:39], v[202:205], v[164:167], v[36:39]
	v_mfma_f32_16x16x32_bf16 v[32:35], v[210:213], v[164:167], v[32:35]
	v_mfma_f32_16x16x32_bf16 v[20:23], v[202:205], v[172:175], v[20:23]
	v_mfma_f32_16x16x32_bf16 v[16:19], v[210:213], v[172:175], v[16:19]
	v_mfma_f32_16x16x32_bf16 v[4:7], v[202:205], v[194:197], v[4:7]
	v_mfma_f32_16x16x32_bf16 v[0:3], v[210:213], v[194:197], v[0:3]
	s_setprio 0
	s_add_i32 s44, 0, 0x18000
	v_add_u32_e32 v140, s44, v240
	s_barrier
	ds_read_b128 v[128:131], v140
	ds_read_b128 v[132:135], v140 offset:1024
	ds_read_b128 v[136:139], v140 offset:2048
	ds_read_b128 v[140:143], v140 offset:3072
	s_add_u32 s42, s42, 0x40000
	s_addc_u32 s43, s43, 0
	s_mov_b32 m0, s61
	v_lshl_add_u64 v[198:199], s[42:43], 0, v[144:145]
	ds_read_b128 v[152:155], v241 offset:32768
	ds_read_b128 v[156:159], v241 offset:33792
	ds_read_b128 v[160:163], v241 offset:34816
	ds_read_b128 v[164:167], v241 offset:35840
	ds_read_b128 v[168:171], v241 offset:36864
	ds_read_b128 v[172:175], v241 offset:37888
	ds_read_b128 v[190:193], v241 offset:38912
	ds_read_b128 v[194:197], v241 offset:39936
	global_load_lds_dwordx4 v[198:199], off
	v_lshl_add_u64 v[198:199], s[42:43], 0, v[146:147]
	s_mov_b32 m0, s62
	s_nop 0
	global_load_lds_dwordx4 v[198:199], off
	s_waitcnt lgkmcnt(8)
	s_barrier
	s_waitcnt lgkmcnt(0)
	s_setprio 1
	s_waitcnt lgkmcnt(0)
	v_mfma_f32_16x16x32_bf16 v[124:127], v[128:131], v[152:155], v[124:127]
	v_mfma_f32_16x16x32_bf16 v[120:123], v[136:139], v[152:155], v[120:123]
	v_mfma_f32_16x16x32_bf16 v[108:111], v[128:131], v[160:163], v[108:111]
	v_mfma_f32_16x16x32_bf16 v[104:107], v[136:139], v[160:163], v[104:107]
	v_mfma_f32_16x16x32_bf16 v[92:95], v[128:131], v[168:171], v[92:95]
	v_mfma_f32_16x16x32_bf16 v[88:91], v[136:139], v[168:171], v[88:91]
	v_mfma_f32_16x16x32_bf16 v[76:79], v[128:131], v[190:193], v[76:79]
	v_mfma_f32_16x16x32_bf16 v[72:75], v[136:139], v[190:193], v[72:75]
	v_mfma_f32_16x16x32_bf16 v[124:127], v[132:135], v[156:159], v[124:127]
	v_mfma_f32_16x16x32_bf16 v[120:123], v[140:143], v[156:159], v[120:123]
	v_mfma_f32_16x16x32_bf16 v[108:111], v[132:135], v[164:167], v[108:111]
	v_mfma_f32_16x16x32_bf16 v[104:107], v[140:143], v[164:167], v[104:107]
	v_mfma_f32_16x16x32_bf16 v[92:95], v[132:135], v[172:175], v[92:95]
	v_mfma_f32_16x16x32_bf16 v[88:91], v[140:143], v[172:175], v[88:91]
	v_mfma_f32_16x16x32_bf16 v[76:79], v[132:135], v[194:197], v[76:79]
	v_mfma_f32_16x16x32_bf16 v[72:75], v[140:143], v[194:197], v[72:75]
	s_setprio 0
	s_barrier
	s_add_i32 s42, 0, 0x1c000
	s_add_i32 s43, s44, s58
	v_add_u32_e32 v176, s42, v240
	v_lshl_add_u64 v[214:215], v[214:215], 0, s[24:25]
	s_mov_b32 m0, s43
	ds_read_b128 v[198:201], v176
	ds_read_b128 v[202:205], v176 offset:1024
	ds_read_b128 v[206:209], v176 offset:2048
	ds_read_b128 v[210:213], v176 offset:3072
	global_load_lds_dwordx4 v[214:215], off
	v_lshl_add_u64 v[214:215], v[216:217], 0, s[24:25]
	s_add_i32 m0, s43, 0x2000
	s_nop 0
	global_load_lds_dwordx4 v[214:215], off
	s_barrier
	s_waitcnt lgkmcnt(0)
	s_setprio 1
	s_waitcnt lgkmcnt(0)
	v_mfma_f32_16x16x32_bf16 v[116:119], v[198:201], v[152:155], v[116:119]
	v_mfma_f32_16x16x32_bf16 v[112:115], v[206:209], v[152:155], v[112:115]
	v_mfma_f32_16x16x32_bf16 v[100:103], v[198:201], v[160:163], v[100:103]
	v_mfma_f32_16x16x32_bf16 v[96:99], v[206:209], v[160:163], v[96:99]
	v_mfma_f32_16x16x32_bf16 v[84:87], v[198:201], v[168:171], v[84:87]
	v_mfma_f32_16x16x32_bf16 v[80:83], v[206:209], v[168:171], v[80:83]
	v_mfma_f32_16x16x32_bf16 v[68:71], v[198:201], v[190:193], v[68:71]
	v_mfma_f32_16x16x32_bf16 v[64:67], v[206:209], v[190:193], v[64:67]
	v_mfma_f32_16x16x32_bf16 v[116:119], v[202:205], v[156:159], v[116:119]
	v_mfma_f32_16x16x32_bf16 v[112:115], v[210:213], v[156:159], v[112:115]
	v_mfma_f32_16x16x32_bf16 v[100:103], v[202:205], v[164:167], v[100:103]
	v_mfma_f32_16x16x32_bf16 v[96:99], v[210:213], v[164:167], v[96:99]
	v_mfma_f32_16x16x32_bf16 v[84:87], v[202:205], v[172:175], v[84:87]
	v_mfma_f32_16x16x32_bf16 v[80:83], v[210:213], v[172:175], v[80:83]
	v_mfma_f32_16x16x32_bf16 v[68:71], v[202:205], v[194:197], v[68:71]
	v_mfma_f32_16x16x32_bf16 v[64:67], v[210:213], v[194:197], v[64:67]
	s_setprio 0
	s_mov_b32 m0, s64
	v_lshl_add_u64 v[214:215], v[218:219], 0, s[24:25]
	s_barrier
	ds_read_b128 v[152:155], v241 offset:49152
	ds_read_b128 v[156:159], v241 offset:50176
	ds_read_b128 v[160:163], v241 offset:51200
	ds_read_b128 v[164:167], v241 offset:52224
	ds_read_b128 v[168:171], v241 offset:53248
	ds_read_b128 v[172:175], v241 offset:54272
	ds_read_b128 v[190:193], v241 offset:55296
	ds_read_b128 v[194:197], v241 offset:56320
	global_load_lds_dwordx4 v[214:215], off
	v_lshl_add_u64 v[214:215], v[220:221], 0, s[24:25]
	s_mov_b32 m0, s65
	s_nop 0
	global_load_lds_dwordx4 v[214:215], off
	s_barrier
	s_waitcnt lgkmcnt(0)
	s_setprio 1
	s_waitcnt lgkmcnt(0)
	v_mfma_f32_16x16x32_bf16 v[60:63], v[128:131], v[152:155], v[60:63]
	v_mfma_f32_16x16x32_bf16 v[56:59], v[136:139], v[152:155], v[56:59]
	v_mfma_f32_16x16x32_bf16 v[44:47], v[128:131], v[160:163], v[44:47]
	v_mfma_f32_16x16x32_bf16 v[40:43], v[136:139], v[160:163], v[40:43]
	v_mfma_f32_16x16x32_bf16 v[28:31], v[128:131], v[168:171], v[28:31]
	v_mfma_f32_16x16x32_bf16 v[24:27], v[136:139], v[168:171], v[24:27]
	v_mfma_f32_16x16x32_bf16 v[12:15], v[128:131], v[190:193], v[12:15]
	v_mfma_f32_16x16x32_bf16 v[8:11], v[136:139], v[190:193], v[8:11]
	v_mfma_f32_16x16x32_bf16 v[60:63], v[132:135], v[156:159], v[60:63]
	v_mfma_f32_16x16x32_bf16 v[56:59], v[140:143], v[156:159], v[56:59]
	v_mfma_f32_16x16x32_bf16 v[44:47], v[132:135], v[164:167], v[44:47]
	v_mfma_f32_16x16x32_bf16 v[40:43], v[140:143], v[164:167], v[40:43]
	v_mfma_f32_16x16x32_bf16 v[28:31], v[132:135], v[172:175], v[28:31]
	v_mfma_f32_16x16x32_bf16 v[24:27], v[140:143], v[172:175], v[24:27]
	v_mfma_f32_16x16x32_bf16 v[12:15], v[132:135], v[194:197], v[12:15]
	v_mfma_f32_16x16x32_bf16 v[8:11], v[140:143], v[194:197], v[8:11]
	s_setprio 0
	s_barrier
	s_add_u32 s38, s38, 0x40080
	s_addc_u32 s39, s39, 0
	s_add_i32 s42, s42, s58
	v_lshl_add_u64 v[128:129], s[38:39], 0, v[144:145]
	s_mov_b32 m0, s42
	s_nop 0
	global_load_lds_dwordx4 v[128:129], off
	v_lshl_add_u64 v[128:129], s[38:39], 0, v[146:147]
	s_add_i32 m0, s42, 0x2000
	s_nop 0
	global_load_lds_dwordx4 v[128:129], off
	s_waitcnt vmcnt(6)
	s_barrier
	s_setprio 1
	v_mfma_f32_16x16x32_bf16 v[52:55], v[198:201], v[152:155], v[52:55]
	v_mfma_f32_16x16x32_bf16 v[48:51], v[206:209], v[152:155], v[48:51]
	v_mfma_f32_16x16x32_bf16 v[36:39], v[198:201], v[160:163], v[36:39]
	v_mfma_f32_16x16x32_bf16 v[32:35], v[206:209], v[160:163], v[32:35]
	v_mfma_f32_16x16x32_bf16 v[20:23], v[198:201], v[168:171], v[20:23]
	v_mfma_f32_16x16x32_bf16 v[16:19], v[206:209], v[168:171], v[16:19]
	v_mfma_f32_16x16x32_bf16 v[4:7], v[198:201], v[190:193], v[4:7]
	v_mfma_f32_16x16x32_bf16 v[0:3], v[206:209], v[190:193], v[0:3]
	v_mfma_f32_16x16x32_bf16 v[52:55], v[202:205], v[156:159], v[52:55]
	v_mfma_f32_16x16x32_bf16 v[48:51], v[210:213], v[156:159], v[48:51]
	v_mfma_f32_16x16x32_bf16 v[36:39], v[202:205], v[164:167], v[36:39]
	v_mfma_f32_16x16x32_bf16 v[32:35], v[210:213], v[164:167], v[32:35]
	v_mfma_f32_16x16x32_bf16 v[20:23], v[202:205], v[172:175], v[20:23]
	v_mfma_f32_16x16x32_bf16 v[16:19], v[210:213], v[172:175], v[16:19]
	v_mfma_f32_16x16x32_bf16 v[4:7], v[202:205], v[194:197], v[4:7]
	v_mfma_f32_16x16x32_bf16 v[0:3], v[210:213], v[194:197], v[0:3]
	s_setprio 0
	s_add_i32 s35, s35, 2
	s_add_u32 s22, s22, 0x100
	s_addc_u32 s23, s23, 0
	s_add_u32 s3, s3, 0x100
	s_addc_u32 s31, s31, 0
	s_cmp_gt_u32 s35, 13
	s_barrier
	s_cbranch_scc0 .LBB0_296
	s_add_u32 s38, s36, 0x40080
	s_addc_u32 s39, s37, 0
	v_lshl_add_u64 v[198:199], s[38:39], 0, v[148:149]
	s_add_i32 m0, s59, 0xc000
	s_nop 0
	global_load_lds_dwordx4 v[198:199], off
	v_lshl_add_u64 v[198:199], s[38:39], 0, v[150:151]
	s_add_i32 m0, s59, 0xe000
	s_nop 0
	global_load_lds_dwordx4 v[198:199], off
	v_mov_b32_e32 v153, v238
	s_mov_b32 s3, s57
	v_mov_b32_e32 v157, v239
	s_mov_b32 s31, s63
	s_lshl_b32 s22, s2, 8
	s_lshl_b32 s3, s3, 6
	s_add_i32 s3, s3, s22
	v_add_u32_e32 v196, s3, v153
	v_readlane_b32 s22, v249, 12
	v_ashrrev_i32_e32 v197, 31, v196
	v_readlane_b32 s23, v249, 13
	v_lshlrev_b32_e32 v200, 2, v157
	v_add_u32_e32 v192, 16, v196
	v_lshl_add_u64 v[128:129], v[196:197], 2, s[22:23]
	global_load_dword v130, v[128:129], off
	global_load_dword v131, v[128:129], off offset:64
	global_load_dword v132, v[128:129], off offset:128
	global_load_dword v133, v[128:129], off offset:192
	global_load_dword v134, v[128:129], off offset:512
	global_load_dword v135, v[128:129], off offset:576
	global_load_dword v136, v[128:129], off offset:640
	s_nop 0
	global_load_dword v128, v[128:129], off offset:704
	v_add_u32_e32 v174, 32, v196
	v_add_u32_e32 v170, 48, v196
	v_add_u32_e32 v166, 0x80, v196
	v_add_u32_e32 v162, 0x90, v196
	v_add_u32_e32 v158, 0xa0, v196
	v_add_u32_e32 v154, 0xb0, v196
	v_ashrrev_i32_e32 v193, 31, v192
	v_ashrrev_i32_e32 v175, 31, v174
	v_ashrrev_i32_e32 v171, 31, v170
	v_ashrrev_i32_e32 v167, 31, v166
	v_ashrrev_i32_e32 v163, 31, v162
	v_ashrrev_i32_e32 v159, 31, v158
	v_ashrrev_i32_e32 v155, 31, v154
	v_lshl_add_u32 v198, s31, 5, v200
	s_cmp_gt_i32 s74, 1
	s_mov_b64 s[22:23], -1
	s_waitcnt vmcnt(0)
	v_fmamk_f32 v129, v130, 0x3a800000, v228
	v_fmamk_f32 v130, v131, 0x3a800000, v228
	v_fmamk_f32 v131, v132, 0x3a800000, v228
	v_fmamk_f32 v132, v133, 0x3a800000, v228
	v_fmamk_f32 v133, v134, 0x3a800000, v228
	v_fmamk_f32 v134, v135, 0x3a800000, v228
	v_fmamk_f32 v135, v136, 0x3a800000, v228
	v_fmamk_f32 v128, v128, 0x3a800000, v228
	v_rsq_f32_e32 v194, v129
	v_rsq_f32_e32 v190, v130
	v_rsq_f32_e32 v172, v131
	v_rsq_f32_e32 v168, v132
	v_rsq_f32_e32 v164, v133
	v_rsq_f32_e32 v160, v134
	v_rsq_f32_e32 v156, v135
	v_rsq_f32_e32 v152, v128
	s_cbranch_scc0 .LBB0_587
	s_cmpk_gt_i32 s2, 0x7f
	s_cselect_b64 s[42:43], -1, 0
	s_cmpk_lt_i32 s2, 0x80
	s_cselect_b64 s[22:23], -1, 0
	s_cmp_lt_u32 s74, 4
	s_cselect_b64 s[38:39], -1, 0
	s_mov_b64 s[2:3], -1
	s_and_b64 vcc, exec, s[38:39]
	s_cbranch_vccnz .LBB0_386
	s_and_b32 s35, s74, 0x7ffffffe
	s_cmp_lt_i32 s35, 16
	s_cbranch_scc1 .LBB0_301
	s_cmp_lg_u32 s35, 16
	s_cselect_b64 s[44:45], -1, 0
	s_cbranch_execz .LBB0_302
	s_branch .LBB0_303

.LBB0_1597:
	v_readlane_b32 s14, v250, 58
	s_mul_i32 s3, s14, 0x10800
	s_waitcnt lgkmcnt(0)
	s_add_u32 s4, s4, s3
	s_addc_u32 s5, s5, 0
	s_mul_i32 s3, s14, 0x5800
	s_add_u32 s6, s6, s3
	s_addc_u32 s7, s7, 0
	s_andn2_b64 vcc, exec, s[12:13]
	v_readlane_b32 s15, v250, 59
	s_cbranch_vccnz .LBB0_1637
	v_ashrrev_i32_e32 v1, 31, v8
	v_lshrrev_b32_e32 v1, 26, v1
	v_add_u32_e32 v1, v8, v1
	v_ashrrev_i32_e32 v9, 6, v1
	v_bfe_i32 v1, v8, 27, 1
	v_lshlrev_b32_e32 v0, 4, v8
	v_lshrrev_b32_e32 v1, 22, v1
	v_add_u32_e32 v1, v0, v1
	v_and_b32_e32 v1, 0xfffffc00, v1
	v_sub_u32_e32 v1, v0, v1
	v_lshrrev_b32_e32 v2, 4, v1
	v_bitop3_b32 v2, v2, v1, 32 bitop3:0x6c
	v_ashrrev_i32_e32 v1, 31, v1
	v_lshrrev_b32_e32 v1, 26, v1
	v_add_u32_e32 v1, v2, v1
	v_ashrrev_i32_e32 v10, 6, v1
	v_mul_i32_i24_e32 v4, 64, v10
	v_sub_u32_e32 v2, v2, v4
	v_lshlrev_b32_e32 v3, 3, v9
	v_lshlrev_b32_e32 v1, 5, v9
	v_ashrrev_i16_sdwa v2, v227, sext(v2) dst_sel:DWORD dst_unused:UNUSED_PAD src0_sel:DWORD src1_sel:BYTE_0
	v_and_b32_e32 v3, 0x1ffff0, v3
	v_and_b32_e32 v1, 32, v1
	v_bfe_i32 v11, v2, 0, 16
	v_add_u32_e32 v1, v1, v11
	v_add_lshl_u32 v2, v10, v3, 11
	v_add_u32_e32 v0, 0x2000, v0
	v_lshl_add_u32 v160, v1, 1, v2
	v_ashrrev_i32_e32 v1, 31, v0
	v_lshrrev_b32_e32 v1, 22, v1
	v_add_u32_e32 v1, v0, v1
	v_ashrrev_i32_e32 v12, 10, v1
	v_mul_i32_i24_e32 v1, 0x400, v12
	v_sub_u32_e32 v0, v0, v1
	v_lshrrev_b32_e32 v1, 4, v0
	v_bitop3_b32 v0, v1, v0, 32 bitop3:0x6c
	v_ashrrev_i32_e32 v2, 31, v0
	v_lshrrev_b32_e32 v2, 26, v2
	v_add_u32_e32 v2, v0, v2
	v_ashrrev_i32_e32 v13, 6, v2
	v_and_b32_e32 v2, 0xc0, v2
	s_ashr_i32 s3, s51, 6
	v_sub_u32_e32 v0, v0, v2
	v_lshlrev_b32_e32 v1, 3, v12
	v_lshlrev_b32_e32 v3, 5, v12
	v_ashrrev_i16_sdwa v0, v227, sext(v0) dst_sel:DWORD dst_unused:UNUSED_PAD src0_sel:DWORD src1_sel:BYTE_0
	s_lshl_b32 s53, s3, 10
	v_and_b32_e32 v1, 0x1ffff0, v1
	v_and_b32_e32 v3, 32, v3
	v_bfe_i32 v14, v0, 0, 16
	s_add_i32 s54, s53, 0
	v_add_u32_e32 v0, v3, v14
	v_add_lshl_u32 v1, v13, v1, 11
	s_add_i32 m0, s54, 0x10000
	v_lshl_add_u32 v162, v0, 1, v1
	s_mov_b32 s101, 1
	global_load_lds_dwordx4 v160, s[44:45]
	s_add_i32 m0, s54, 0x12000
	s_ashr_i32 s52, s51, 8
	global_load_lds_dwordx4 v162, s[44:45]
	s_mov_b32 m0, s54
	s_add_i32 s55, s54, 0x2000
	global_load_lds_dwordx4 v160, s[42:43]
	s_mov_b32 m0, s55
	s_add_u32 s12, s44, 0x40000
	global_load_lds_dwordx4 v162, s[42:43]
	s_addc_u32 s13, s45, 0
	s_add_i32 m0, s54, 0x14000
	v_mov_b32_e32 v161, v177
	global_load_lds_dwordx4 v160, s[12:13]
	s_add_i32 m0, s54, 0x16000
	v_mov_b32_e32 v163, v177
	global_load_lds_dwordx4 v162, s[12:13]
	s_add_u32 s12, s42, 0x40000
	s_addc_u32 s13, s43, 0
	s_add_i32 s56, s54, 0x4000
	s_mov_b32 m0, s56
	s_add_i32 s57, s54, 0x6000
	global_load_lds_dwordx4 v160, s[12:13]
	s_mov_b32 m0, s57
	v_lshl_add_u64 v[6:7], s[44:45], 0, v[160:161]
	global_load_lds_dwordx4 v162, s[12:13]
	v_lshl_add_u64 v[4:5], s[44:45], 0, v[162:163]
	v_lshl_add_u64 v[2:3], s[42:43], 0, v[160:161]
	s_cmp_lg_u32 s52, 1
	v_lshl_add_u64 v[0:1], s[42:43], 0, v[162:163]
	s_cbranch_scc1 .LBB0_1600
	s_barrier

.LBB0_1601:
	s_mov_b32 s101, -2
	s_or_b64 exec, exec, s[2:3]
	s_and_b64 vcc, exec, s[40:41]
	s_mov_b32 s48, s18
	s_mov_b32 s2, s22
	s_mov_b64 s[44:45], s[38:39]
	s_mov_b64 s[42:43], s[36:37]
	s_cbranch_vccnz .LBB0_1634

.LBB0_1609:
	s_add_u32 s44, s42, 0xfffc0080
	s_addc_u32 s45, s43, -1
	s_add_i32 s49, 0, 0x10000
	v_add_u32_e32 v116, s49, v238
	ds_read_b128 v[104:107], v116
	ds_read_b128 v[108:111], v116 offset:1024
	ds_read_b128 v[112:115], v116 offset:2048
	ds_read_b128 v[116:119], v116 offset:3072
	s_cmp_eq_u32 s23, 12
	s_cselect_b32 s47, s37, s45
	s_cselect_b32 s46, s36, s44
	s_cselect_b32 s45, s39, s19
	s_cselect_b32 s44, s38, s3
	v_lshl_add_u64 v[198:199], s[42:43], 0, v[164:165]
	s_add_i32 m0, s54, 0xc000
	ds_read_b128 v[120:123], v239
	ds_read_b128 v[124:127], v239 offset:1024
	ds_read_b128 v[128:131], v239 offset:2048
	ds_read_b128 v[132:135], v239 offset:3072
	ds_read_b128 v[168:171], v239 offset:4096
	ds_read_b128 v[172:175], v239 offset:5120
	ds_read_b128 v[190:193], v239 offset:6144
	ds_read_b128 v[194:197], v239 offset:7168
	s_cmp_eq_u32 s23, s101
	s_cbranch_scc1 .Lhoist_p1_H
	global_load_lds_dwordx4 v[198:199], off
	v_lshl_add_u64 v[198:199], s[42:43], 0, v[166:167]
	s_add_i32 m0, s54, 0xe000
	s_nop 0
	global_load_lds_dwordx4 v[198:199], off
.Lhoist_p1_H:
	s_waitcnt lgkmcnt(8)
	s_barrier
	s_waitcnt lgkmcnt(0)
	s_setprio 1
	s_waitcnt lgkmcnt(0)
	v_mfma_f32_16x16x32_bf16 v[156:159], v[104:107], v[120:123], v[156:159]
	v_mfma_f32_16x16x32_bf16 v[60:63], v[112:115], v[120:123], v[60:63]
	v_mfma_f32_16x16x32_bf16 v[148:151], v[104:107], v[128:131], v[148:151]
	v_mfma_f32_16x16x32_bf16 v[52:55], v[112:115], v[128:131], v[52:55]
	v_mfma_f32_16x16x32_bf16 v[140:143], v[104:107], v[168:171], v[140:143]
	v_mfma_f32_16x16x32_bf16 v[44:47], v[112:115], v[168:171], v[44:47]
	v_mfma_f32_16x16x32_bf16 v[100:103], v[104:107], v[190:193], v[100:103]
	v_mfma_f32_16x16x32_bf16 v[36:39], v[112:115], v[190:193], v[36:39]
	v_mfma_f32_16x16x32_bf16 v[156:159], v[108:111], v[124:127], v[156:159]
	v_mfma_f32_16x16x32_bf16 v[60:63], v[116:119], v[124:127], v[60:63]
	v_mfma_f32_16x16x32_bf16 v[148:151], v[108:111], v[132:135], v[148:151]
	v_mfma_f32_16x16x32_bf16 v[52:55], v[116:119], v[132:135], v[52:55]
	v_mfma_f32_16x16x32_bf16 v[140:143], v[108:111], v[172:175], v[140:143]
	v_mfma_f32_16x16x32_bf16 v[44:47], v[116:119], v[172:175], v[44:47]
	v_mfma_f32_16x16x32_bf16 v[100:103], v[108:111], v[194:197], v[100:103]
	v_mfma_f32_16x16x32_bf16 v[36:39], v[116:119], v[194:197], v[36:39]
	s_setprio 0
	s_barrier
	s_add_i32 s63, 0, 0x14000
	s_add_i32 s49, s49, s53
	v_add_u32_e32 v176, s63, v238
	v_lshl_add_u64 v[218:219], s[44:45], 0, v[160:161]
	s_mov_b32 m0, s49
	ds_read_b128 v[198:201], v176
	ds_read_b128 v[202:205], v176 offset:1024
	ds_read_b128 v[206:209], v176 offset:2048
	ds_read_b128 v[210:213], v176 offset:3072
	global_load_lds_dwordx4 v[218:219], off
	v_lshl_add_u64 v[220:221], s[44:45], 0, v[162:163]
	s_add_i32 m0, s49, 0x2000
	s_nop 0
	global_load_lds_dwordx4 v[220:221], off
	s_barrier
	s_waitcnt lgkmcnt(0)
	s_setprio 1
	s_waitcnt lgkmcnt(0)
	v_mfma_f32_16x16x32_bf16 v[152:155], v[198:201], v[120:123], v[152:155]
	v_mfma_f32_16x16x32_bf16 v[56:59], v[206:209], v[120:123], v[56:59]
	v_mfma_f32_16x16x32_bf16 v[48:51], v[206:209], v[128:131], v[48:51]
	v_mfma_f32_16x16x32_bf16 v[40:43], v[206:209], v[168:171], v[40:43]
	v_mfma_f32_16x16x32_bf16 v[96:99], v[198:201], v[190:193], v[96:99]
	v_mfma_f32_16x16x32_bf16 v[32:35], v[206:209], v[190:193], v[32:35]
	v_mfma_f32_16x16x32_bf16 v[152:155], v[202:205], v[124:127], v[152:155]
	v_mfma_f32_16x16x32_bf16 v[56:59], v[210:213], v[124:127], v[56:59]
	v_mfma_f32_16x16x32_bf16 v[120:123], v[198:201], v[128:131], v[144:147]
	v_mfma_f32_16x16x32_bf16 v[48:51], v[210:213], v[132:135], v[48:51]
	v_mfma_f32_16x16x32_bf16 v[124:127], v[198:201], v[168:171], v[136:139]
	v_mfma_f32_16x16x32_bf16 v[40:43], v[210:213], v[172:175], v[40:43]
	v_mfma_f32_16x16x32_bf16 v[96:99], v[202:205], v[194:197], v[96:99]
	v_mfma_f32_16x16x32_bf16 v[32:35], v[210:213], v[194:197], v[32:35]
	v_mfma_f32_16x16x32_bf16 v[120:123], v[202:205], v[132:135], v[120:123]
	v_mfma_f32_16x16x32_bf16 v[124:127], v[202:205], v[172:175], v[124:127]
	s_setprio 0
	s_mov_b32 m0, s54
	v_lshl_add_u64 v[240:241], s[46:47], 0, v[160:161]
	s_barrier
	ds_read_b128 v[128:131], v239 offset:16384
	ds_read_b128 v[132:135], v239 offset:17408
	ds_read_b128 v[136:139], v239 offset:18432
	ds_read_b128 v[144:147], v239 offset:19456
	ds_read_b128 v[168:171], v239 offset:20480
	ds_read_b128 v[172:175], v239 offset:21504
	ds_read_b128 v[190:193], v239 offset:22528
	ds_read_b128 v[194:197], v239 offset:23552
	global_load_lds_dwordx4 v[240:241], off
	v_lshl_add_u64 v[242:243], s[46:47], 0, v[162:163]
	s_mov_b32 m0, s55
	s_nop 0
	global_load_lds_dwordx4 v[242:243], off
	s_barrier
	s_waitcnt lgkmcnt(0)
	s_setprio 1
	s_waitcnt lgkmcnt(0)
	v_mfma_f32_16x16x32_bf16 v[92:95], v[104:107], v[128:131], v[92:95]
	v_mfma_f32_16x16x32_bf16 v[28:31], v[112:115], v[128:131], v[28:31]
	v_mfma_f32_16x16x32_bf16 v[84:87], v[104:107], v[136:139], v[84:87]
	v_mfma_f32_16x16x32_bf16 v[20:23], v[112:115], v[136:139], v[20:23]
	v_mfma_f32_16x16x32_bf16 v[76:79], v[104:107], v[168:171], v[76:79]
	v_mfma_f32_16x16x32_bf16 v[12:15], v[112:115], v[168:171], v[12:15]
	v_mfma_f32_16x16x32_bf16 v[68:71], v[104:107], v[190:193], v[68:71]
	v_mfma_f32_16x16x32_bf16 v[4:7], v[112:115], v[190:193], v[4:7]
	v_mfma_f32_16x16x32_bf16 v[92:95], v[108:111], v[132:135], v[92:95]
	v_mfma_f32_16x16x32_bf16 v[28:31], v[116:119], v[132:135], v[28:31]
	v_mfma_f32_16x16x32_bf16 v[84:87], v[108:111], v[144:147], v[84:87]
	v_mfma_f32_16x16x32_bf16 v[20:23], v[116:119], v[144:147], v[20:23]
	v_mfma_f32_16x16x32_bf16 v[76:79], v[108:111], v[172:175], v[76:79]
	v_mfma_f32_16x16x32_bf16 v[12:15], v[116:119], v[172:175], v[12:15]
	v_mfma_f32_16x16x32_bf16 v[68:71], v[108:111], v[194:197], v[68:71]
	v_mfma_f32_16x16x32_bf16 v[4:7], v[116:119], v[194:197], v[4:7]
	s_setprio 0
	s_barrier
	s_add_u32 s64, s44, 0x40000
	s_addc_u32 s65, s45, 0
	s_add_i32 s49, s63, s53
	v_lshl_add_u64 v[104:105], s[64:65], 0, v[160:161]
	s_mov_b32 m0, s49
	s_nop 0
	global_load_lds_dwordx4 v[104:105], off
	v_lshl_add_u64 v[104:105], s[64:65], 0, v[162:163]
	s_add_i32 m0, s49, 0x2000
	s_nop 0
	global_load_lds_dwordx4 v[104:105], off
	s_cmp_eq_u32 s23, s101
	s_cbranch_scc1 .Lhoist_p4_H
	s_waitcnt vmcnt(6)
.Lhoist_p4_H:
	s_barrier
	s_setprio 1
	v_mfma_f32_16x16x32_bf16 v[88:91], v[198:201], v[128:131], v[88:91]
	v_mfma_f32_16x16x32_bf16 v[24:27], v[206:209], v[128:131], v[24:27]
	v_mfma_f32_16x16x32_bf16 v[80:83], v[198:201], v[136:139], v[80:83]
	v_mfma_f32_16x16x32_bf16 v[16:19], v[206:209], v[136:139], v[16:19]
	v_mfma_f32_16x16x32_bf16 v[72:75], v[198:201], v[168:171], v[72:75]
	v_mfma_f32_16x16x32_bf16 v[8:11], v[206:209], v[168:171], v[8:11]
	v_mfma_f32_16x16x32_bf16 v[64:67], v[198:201], v[190:193], v[64:67]
	v_mfma_f32_16x16x32_bf16 v[0:3], v[206:209], v[190:193], v[0:3]
	v_mfma_f32_16x16x32_bf16 v[88:91], v[202:205], v[132:135], v[88:91]
	v_mfma_f32_16x16x32_bf16 v[24:27], v[210:213], v[132:135], v[24:27]
	v_mfma_f32_16x16x32_bf16 v[80:83], v[202:205], v[144:147], v[80:83]
	v_mfma_f32_16x16x32_bf16 v[16:19], v[210:213], v[144:147], v[16:19]
	v_mfma_f32_16x16x32_bf16 v[72:75], v[202:205], v[172:175], v[72:75]
	v_mfma_f32_16x16x32_bf16 v[8:11], v[210:213], v[172:175], v[8:11]
	v_mfma_f32_16x16x32_bf16 v[64:67], v[202:205], v[194:197], v[64:67]
	v_mfma_f32_16x16x32_bf16 v[0:3], v[210:213], v[194:197], v[0:3]
	s_setprio 0
	s_add_i32 s49, 0, 0x18000
	v_add_u32_e32 v116, s49, v238
	s_barrier
	ds_read_b128 v[104:107], v116
	ds_read_b128 v[108:111], v116 offset:1024
	ds_read_b128 v[112:115], v116 offset:2048
	ds_read_b128 v[116:119], v116 offset:3072
	s_add_u32 s46, s46, 0x40000
	s_addc_u32 s47, s47, 0
	s_mov_b32 m0, s56
	v_lshl_add_u64 v[144:145], s[46:47], 0, v[160:161]
	ds_read_b128 v[128:131], v239 offset:32768
	ds_read_b128 v[132:135], v239 offset:33792
	ds_read_b128 v[136:139], v239 offset:34816
	ds_read_b128 v[168:171], v239 offset:35840
	ds_read_b128 v[172:175], v239 offset:36864
	ds_read_b128 v[190:193], v239 offset:37888
	ds_read_b128 v[194:197], v239 offset:38912
	ds_read_b128 v[198:201], v239 offset:39936
	global_load_lds_dwordx4 v[144:145], off
	v_lshl_add_u64 v[144:145], s[46:47], 0, v[162:163]
	s_mov_b32 m0, s57
	s_nop 0
	global_load_lds_dwordx4 v[144:145], off
	s_waitcnt lgkmcnt(8)
	s_barrier
	s_waitcnt lgkmcnt(0)
	s_setprio 1
	s_waitcnt lgkmcnt(0)
	v_mfma_f32_16x16x32_bf16 v[144:147], v[104:107], v[128:131], v[156:159]
	v_mfma_f32_16x16x32_bf16 v[156:159], v[108:111], v[132:135], v[144:147]
	v_mfma_f32_16x16x32_bf16 v[60:63], v[112:115], v[128:131], v[60:63]
	v_mfma_f32_16x16x32_bf16 v[144:147], v[104:107], v[136:139], v[148:151]
	v_mfma_f32_16x16x32_bf16 v[52:55], v[112:115], v[136:139], v[52:55]
	v_mfma_f32_16x16x32_bf16 v[140:143], v[104:107], v[172:175], v[140:143]
	v_mfma_f32_16x16x32_bf16 v[44:47], v[112:115], v[172:175], v[44:47]
	v_mfma_f32_16x16x32_bf16 v[100:103], v[104:107], v[194:197], v[100:103]
	v_mfma_f32_16x16x32_bf16 v[36:39], v[112:115], v[194:197], v[36:39]
	v_mfma_f32_16x16x32_bf16 v[60:63], v[116:119], v[132:135], v[60:63]
	v_mfma_f32_16x16x32_bf16 v[148:151], v[108:111], v[168:171], v[144:147]
	v_mfma_f32_16x16x32_bf16 v[52:55], v[116:119], v[168:171], v[52:55]
	v_mfma_f32_16x16x32_bf16 v[140:143], v[108:111], v[190:193], v[140:143]
	v_mfma_f32_16x16x32_bf16 v[44:47], v[116:119], v[190:193], v[44:47]
	v_mfma_f32_16x16x32_bf16 v[100:103], v[108:111], v[198:201], v[100:103]
	v_mfma_f32_16x16x32_bf16 v[36:39], v[116:119], v[198:201], v[36:39]
	s_setprio 0
	s_barrier
	s_add_i32 s46, 0, 0x1c000
	v_add_u32_e32 v144, s46, v238
	s_add_i32 s47, s49, s53
	ds_read_b128 v[202:205], v144
	ds_read_b128 v[206:209], v144 offset:1024
	ds_read_b128 v[210:213], v144 offset:2048
	ds_read_b128 v[214:217], v144 offset:3072
	v_lshl_add_u64 v[144:145], v[218:219], 0, s[24:25]
	s_mov_b32 m0, s47
	s_nop 0
	global_load_lds_dwordx4 v[144:145], off
	v_lshl_add_u64 v[144:145], v[220:221], 0, s[24:25]
	s_add_i32 m0, s47, 0x2000
	s_nop 0
	global_load_lds_dwordx4 v[144:145], off
	s_barrier
	s_waitcnt lgkmcnt(0)
	s_setprio 1
	s_waitcnt lgkmcnt(0)
	v_mfma_f32_16x16x32_bf16 v[144:147], v[202:205], v[128:131], v[152:155]
	v_mfma_f32_16x16x32_bf16 v[120:123], v[202:205], v[136:139], v[120:123]
	v_mfma_f32_16x16x32_bf16 v[152:155], v[206:209], v[132:135], v[144:147]
	v_mfma_f32_16x16x32_bf16 v[56:59], v[210:213], v[128:131], v[56:59]
	v_mfma_f32_16x16x32_bf16 v[144:147], v[206:209], v[168:171], v[120:123]
	v_mfma_f32_16x16x32_bf16 v[48:51], v[210:213], v[136:139], v[48:51]
	v_mfma_f32_16x16x32_bf16 v[120:123], v[202:205], v[172:175], v[124:127]
	v_mfma_f32_16x16x32_bf16 v[40:43], v[210:213], v[172:175], v[40:43]
	v_mfma_f32_16x16x32_bf16 v[96:99], v[202:205], v[194:197], v[96:99]
	v_mfma_f32_16x16x32_bf16 v[32:35], v[210:213], v[194:197], v[32:35]
	v_mfma_f32_16x16x32_bf16 v[56:59], v[214:217], v[132:135], v[56:59]
	v_mfma_f32_16x16x32_bf16 v[48:51], v[214:217], v[168:171], v[48:51]
	v_mfma_f32_16x16x32_bf16 v[136:139], v[206:209], v[190:193], v[120:123]
	v_mfma_f32_16x16x32_bf16 v[40:43], v[214:217], v[190:193], v[40:43]
	v_mfma_f32_16x16x32_bf16 v[96:99], v[206:209], v[198:201], v[96:99]
	v_mfma_f32_16x16x32_bf16 v[32:35], v[214:217], v[198:201], v[32:35]
	s_setprio 0
	s_mov_b32 m0, s59
	v_lshl_add_u64 v[198:199], v[240:241], 0, s[24:25]
	s_barrier
	ds_read_b128 v[120:123], v239 offset:49152
	ds_read_b128 v[124:127], v239 offset:50176
	ds_read_b128 v[128:131], v239 offset:51200
	ds_read_b128 v[132:135], v239 offset:52224
	ds_read_b128 v[168:171], v239 offset:53248
	ds_read_b128 v[172:175], v239 offset:54272
	ds_read_b128 v[190:193], v239 offset:55296
	ds_read_b128 v[194:197], v239 offset:56320
	global_load_lds_dwordx4 v[198:199], off
	v_lshl_add_u64 v[198:199], v[242:243], 0, s[24:25]
	s_mov_b32 m0, s60
	s_nop 0
	global_load_lds_dwordx4 v[198:199], off
	s_barrier
	s_waitcnt lgkmcnt(0)
	s_setprio 1
	s_waitcnt lgkmcnt(0)
	v_mfma_f32_16x16x32_bf16 v[92:95], v[104:107], v[120:123], v[92:95]
	v_mfma_f32_16x16x32_bf16 v[28:31], v[112:115], v[120:123], v[28:31]
	v_mfma_f32_16x16x32_bf16 v[84:87], v[104:107], v[128:131], v[84:87]
	v_mfma_f32_16x16x32_bf16 v[20:23], v[112:115], v[128:131], v[20:23]
	v_mfma_f32_16x16x32_bf16 v[76:79], v[104:107], v[168:171], v[76:79]
	v_mfma_f32_16x16x32_bf16 v[12:15], v[112:115], v[168:171], v[12:15]
	v_mfma_f32_16x16x32_bf16 v[68:71], v[104:107], v[190:193], v[68:71]
	v_mfma_f32_16x16x32_bf16 v[4:7], v[112:115], v[190:193], v[4:7]
	v_mfma_f32_16x16x32_bf16 v[92:95], v[108:111], v[124:127], v[92:95]
	v_mfma_f32_16x16x32_bf16 v[28:31], v[116:119], v[124:127], v[28:31]
	v_mfma_f32_16x16x32_bf16 v[84:87], v[108:111], v[132:135], v[84:87]
	v_mfma_f32_16x16x32_bf16 v[20:23], v[116:119], v[132:135], v[20:23]
	v_mfma_f32_16x16x32_bf16 v[76:79], v[108:111], v[172:175], v[76:79]
	v_mfma_f32_16x16x32_bf16 v[12:15], v[116:119], v[172:175], v[12:15]
	v_mfma_f32_16x16x32_bf16 v[68:71], v[108:111], v[194:197], v[68:71]
	v_mfma_f32_16x16x32_bf16 v[4:7], v[116:119], v[194:197], v[4:7]
	s_setprio 0
	s_barrier
	s_add_u32 s44, s44, 0x40080
	s_addc_u32 s45, s45, 0
	s_add_i32 s46, s46, s53
	v_lshl_add_u64 v[104:105], s[44:45], 0, v[160:161]
	s_mov_b32 m0, s46
	s_nop 0
	global_load_lds_dwordx4 v[104:105], off
	v_lshl_add_u64 v[104:105], s[44:45], 0, v[162:163]
	s_add_i32 m0, s46, 0x2000
	s_nop 0
	global_load_lds_dwordx4 v[104:105], off
	s_waitcnt vmcnt(6)
	s_barrier
	s_setprio 1
	v_mfma_f32_16x16x32_bf16 v[88:91], v[202:205], v[120:123], v[88:91]
	v_mfma_f32_16x16x32_bf16 v[24:27], v[210:213], v[120:123], v[24:27]
	v_mfma_f32_16x16x32_bf16 v[80:83], v[202:205], v[128:131], v[80:83]
	v_mfma_f32_16x16x32_bf16 v[16:19], v[210:213], v[128:131], v[16:19]
	v_mfma_f32_16x16x32_bf16 v[72:75], v[202:205], v[168:171], v[72:75]
	v_mfma_f32_16x16x32_bf16 v[8:11], v[210:213], v[168:171], v[8:11]
	v_mfma_f32_16x16x32_bf16 v[64:67], v[202:205], v[190:193], v[64:67]
	v_mfma_f32_16x16x32_bf16 v[0:3], v[210:213], v[190:193], v[0:3]
	v_mfma_f32_16x16x32_bf16 v[88:91], v[206:209], v[124:127], v[88:91]
	v_mfma_f32_16x16x32_bf16 v[24:27], v[214:217], v[124:127], v[24:27]
	v_mfma_f32_16x16x32_bf16 v[80:83], v[206:209], v[132:135], v[80:83]
	v_mfma_f32_16x16x32_bf16 v[16:19], v[214:217], v[132:135], v[16:19]
	v_mfma_f32_16x16x32_bf16 v[72:75], v[206:209], v[172:175], v[72:75]
	v_mfma_f32_16x16x32_bf16 v[8:11], v[214:217], v[172:175], v[8:11]
	v_mfma_f32_16x16x32_bf16 v[64:67], v[206:209], v[194:197], v[64:67]
	v_mfma_f32_16x16x32_bf16 v[0:3], v[214:217], v[194:197], v[0:3]
	s_setprio 0
	s_add_i32 s23, s23, 2
	s_add_u32 s42, s42, 0x100
	s_addc_u32 s43, s43, 0
	s_add_u32 s3, s3, 0x100
	s_addc_u32 s19, s19, 0
	s_cmp_gt_u32 s23, 13
	s_barrier
	s_cbranch_scc0 .LBB0_1609
	s_add_u32 s44, s36, 0x40080
	s_addc_u32 s45, s37, 0
	v_lshl_add_u64 v[198:199], s[44:45], 0, v[164:165]
	s_add_i32 m0, s54, 0xc000
	s_nop 0
	global_load_lds_dwordx4 v[198:199], off
	v_lshl_add_u64 v[198:199], s[44:45], 0, v[166:167]
	s_add_i32 m0, s54, 0xe000
	s_nop 0
	global_load_lds_dwordx4 v[198:199], off
	v_mov_b32_e32 v106, v223
	s_mov_b32 s3, s58
	v_mov_b32_e32 v200, v222
	s_mov_b32 s19, s52
	s_lshl_b32 s23, s2, 8
	s_lshl_b32 s42, s19, 6
	s_add_i32 s42, s42, s23
	s_lshl_b32 s23, s48, 7
	s_lshl_b32 s3, s3, 5
	s_add_i32 s3, s3, s23
	v_lshl_add_u32 v170, v106, 2, s3
	v_ashrrev_i32_e32 v171, 31, v170
	v_lshlrev_b64 v[106:107], 2, v[170:171]
	v_add_u32_e32 v104, s42, v200
	v_lshl_add_u64 v[192:193], s[4:5], 0, v[106:107]
	s_movk_i32 s3, 0x2000
	v_ashrrev_i32_e32 v105, 31, v104
	v_add_co_u32_e32 v120, vcc, s3, v192
	v_lshl_add_u64 v[104:105], v[104:105], 2, s[10:11]
	v_lshl_add_u64 v[190:191], s[14:15], 0, v[106:107]
	v_addc_co_u32_e32 v121, vcc, 0, v193, vcc
	global_load_dword v168, v[104:105], off
	v_add_co_u32_e32 v124, vcc, s3, v190
	v_lshl_add_u64 v[174:175], s[16:17], 0, v[106:107]
	s_nop 0
	v_addc_co_u32_e32 v125, vcc, 0, v191, vcc
	v_add_co_u32_e32 v128, vcc, s3, v174
	v_lshl_add_u64 v[172:173], s[6:7], 0, v[106:107]
	s_nop 0
	v_addc_co_u32_e32 v129, vcc, 0, v175, vcc
	v_add_co_u32_e32 v132, vcc, s3, v172
	global_load_dword v245, v[104:105], off offset:64
	global_load_dword v244, v[104:105], off offset:128
	global_load_dword v176, v[104:105], off offset:192
	global_load_dword v243, v[104:105], off offset:512
	global_load_dword v242, v[104:105], off offset:576
	global_load_dword v241, v[104:105], off offset:640
	global_load_dword v169, v[104:105], off offset:704
	v_addc_co_u32_e32 v133, vcc, 0, v173, vcc
	global_load_dwordx4 v[104:107], v[192:193], off
	global_load_dwordx4 v[108:111], v[190:191], off
	global_load_dwordx4 v[112:115], v[174:175], off
	global_load_dwordx4 v[116:119], v[172:173], off
	s_nop 0
	global_load_dwordx4 v[120:123], v[120:121], off offset:3072
	s_nop 0
	global_load_dwordx4 v[124:127], v[124:125], off offset:3072
	s_nop 0
	global_load_dwordx4 v[128:131], v[128:129], off offset:3072
	s_nop 0
	global_load_dwordx4 v[132:135], v[132:133], off offset:3072
	s_lshl_b32 s2, s2, 2
	v_readlane_b32 s42, v249, 58
	s_add_i32 s2, s19, s2
	v_readlane_b32 s43, v249, 59
	v_cmp_lt_i32_e64 s[44:45], 1, v200
	v_lshl_add_u32 v240, s2, 6, v200
	v_lshl_add_u64 v[196:197], v[170:171], 1, s[42:43]
	s_waitcnt vmcnt(0)
	v_fmamk_f32 v168, v168, 0x3a800000, v228
	v_rsq_f32_e32 v168, v168
	s_nop 0
	v_pk_mul_f32 v[208:209], v[156:157], v[168:169] op_sel_hi:[1,0]
	v_pk_mul_f32 v[204:205], v[152:153], v[168:169] op_sel_hi:[1,0]
	v_pk_mul_f32 v[206:207], v[158:159], v[168:169] op_sel_hi:[1,0]
	v_pk_mul_f32 v[210:211], v[154:155], v[168:169] op_sel_hi:[1,0]
	v_mov_b32_dpp v194, v208 row_ror:1 row_mask:0xf bank_mask:0xf
	v_mov_b32_dpp v202, v208 row_ror:2 row_mask:0xf bank_mask:0xf
	v_mov_b32_dpp v195, v209 row_ror:1 row_mask:0xf bank_mask:0xf
	v_mov_b32_dpp v203, v209 row_ror:2 row_mask:0xf bank_mask:0xf
	v_mov_b32_dpp v214, v204 row_ror:1 row_mask:0xf bank_mask:0xf
	v_mov_b32_dpp v216, v204 row_ror:2 row_mask:0xf bank_mask:0xf
	v_mov_b32_dpp v215, v205 row_ror:1 row_mask:0xf bank_mask:0xf
	v_mov_b32_dpp v217, v205 row_ror:2 row_mask:0xf bank_mask:0xf
	v_mov_b32_dpp v198, v206 row_ror:1 row_mask:0xf bank_mask:0xf
	v_mov_b32_dpp v212, v206 row_ror:2 row_mask:0xf bank_mask:0xf
	v_mov_b32_dpp v199, v207 row_ror:1 row_mask:0xf bank_mask:0xf
	v_mov_b32_dpp v213, v207 row_ror:2 row_mask:0xf bank_mask:0xf
	v_mov_b32_dpp v218, v210 row_ror:1 row_mask:0xf bank_mask:0xf
	v_mov_b32_dpp v220, v210 row_ror:2 row_mask:0xf bank_mask:0xf
	v_mov_b32_dpp v219, v211 row_ror:1 row_mask:0xf bank_mask:0xf
	v_mov_b32_dpp v221, v211 row_ror:2 row_mask:0xf bank_mask:0xf
	v_mov_b32_dpp v194, v208 row_shr:1 row_mask:0xf bank_mask:0xf
	v_mov_b32_dpp v202, v208 row_shr:2 row_mask:0xf bank_mask:0xf
	v_mov_b32_dpp v195, v209 row_shr:1 row_mask:0xf bank_mask:0xf
	v_mov_b32_dpp v203, v209 row_shr:2 row_mask:0xf bank_mask:0xf
	v_mov_b32_dpp v214, v204 row_shr:1 row_mask:0xf bank_mask:0xf
	v_mov_b32_dpp v216, v204 row_shr:2 row_mask:0xf bank_mask:0xf
	v_mov_b32_dpp v215, v205 row_shr:1 row_mask:0xf bank_mask:0xf
	v_mov_b32_dpp v217, v205 row_shr:2 row_mask:0xf bank_mask:0xf
	v_mov_b32_dpp v198, v206 row_shr:1 row_mask:0xf bank_mask:0xf
	v_mov_b32_dpp v212, v206 row_shr:2 row_mask:0xf bank_mask:0xf
	v_mov_b32_dpp v199, v207 row_shr:1 row_mask:0xf bank_mask:0xf
	v_mov_b32_dpp v213, v207 row_shr:2 row_mask:0xf bank_mask:0xf
	v_mov_b32_dpp v218, v210 row_shr:1 row_mask:0xf bank_mask:0xf
	v_mov_b32_dpp v220, v210 row_shr:2 row_mask:0xf bank_mask:0xf
	v_mov_b32_dpp v219, v211 row_shr:1 row_mask:0xf bank_mask:0xf
	v_mov_b32_dpp v221, v211 row_shr:2 row_mask:0xf bank_mask:0xf
	s_and_saveexec_b64 s[42:43], s[44:45]
	s_cbranch_execz .LBB0_1612
	v_pk_fma_f32 v[246:247], v[208:209], v[112:113], v[116:117]
	s_movk_i32 s3, 0x1600
	v_pk_fma_f32 v[194:195], v[108:109], v[194:195], v[246:247]
	v_pk_fma_f32 v[246:247], v[204:205], v[128:129], v[132:133]
	v_pk_fma_f32 v[194:195], v[104:105], v[202:203], v[194:195]
	v_pk_fma_f32 v[214:215], v[124:125], v[214:215], v[246:247]
	v_mul_f32_e32 v201, 0xbfb8aa3b, v194
	v_mul_f32_e32 v202, 0xbfb8aa3b, v195
	v_exp_f32_e32 v201, v201
	v_exp_f32_e32 v202, v202
	v_pk_fma_f32 v[214:215], v[120:121], v[216:217], v[214:215]
	v_add_f32_e32 v201, 1.0, v201
	v_add_f32_e32 v203, 1.0, v202
	v_rcp_f32_e32 v202, v201
	v_rcp_f32_e32 v203, v203
	s_nop 0
	v_pk_mul_f32 v[194:195], v[194:195], v[202:203]
	v_pk_fma_f32 v[202:203], v[206:207], v[114:115], v[118:119]
	v_pk_mul_f32 v[194:195], v[194:195], v[214:215]
	v_pk_fma_f32 v[198:199], v[110:111], v[198:199], v[202:203]
	v_cvt_pk_bf16_f32 v194, v194, v195
	v_pk_fma_f32 v[198:199], v[106:107], v[212:213], v[198:199]
	v_pk_fma_f32 v[212:213], v[210:211], v[130:131], v[134:135]
	v_mul_f32_e32 v201, 0xbfb8aa3b, v198
	v_exp_f32_e32 v201, v201
	v_mul_f32_e32 v202, 0xbfb8aa3b, v199
	v_exp_f32_e32 v203, v202
	v_pk_fma_f32 v[212:213], v[126:127], v[218:219], v[212:213]
	v_add_f32_e32 v201, 1.0, v201
	v_rcp_f32_e32 v202, v201
	v_add_f32_e32 v201, 1.0, v203
	v_rcp_f32_e32 v203, v201
	v_pk_fma_f32 v[212:213], v[122:123], v[220:221], v[212:213]
	v_pk_mul_f32 v[198:199], v[198:199], v[202:203]
	s_nop 0
	v_pk_mul_f32 v[198:199], v[198:199], v[212:213]
	s_nop 0
	v_cvt_pk_bf16_f32 v195, v198, v199
	v_mad_i64_i32 v[198:199], s[46:47], v240, s3, v[196:197]
	global_store_dwordx2 v[198:199], v[194:195], off
